# plus attention loop: each s_waitcnt lgkmcnt(0) replaced by the counted wait its first consumer needs (K fragments 3 ahead, V fragments 2 blocks ahead stay in flight)
# speedup vs baseline: 1.0109x; 1.0074x over previous
.LBB0_961:
	s_waitcnt vmcnt(5)
	s_barrier
	s_mov_b32 s19, s5
	s_mov_b32 s5, s25
	s_mul_i32 s9, s25, 0x6000
	s_add_i32 s25, s9, 0
	v_add_u32_e32 v124, s25, v225
	ds_read_b128 v[120:123], v124
	ds_read_b128 v[160:163], v124 offset:4096
	ds_read_b128 v[168:171], v124 offset:8192
	ds_read_b128 v[172:175], v124 offset:12288
	s_waitcnt lgkmcnt(3)
	v_mfma_f32_16x16x32_bf16 v[124:127], v[120:123], v[4:7], v[48:51]
	v_exp_f32_e32 v188, v148
	v_exp_f32_e32 v189, v149
	v_mfma_f32_16x16x32_bf16 v[120:123], v[120:123], v[40:43], v[52:55]
	v_add_u32_e32 v196, s25, v234
	ds_read_b128 v[184:187], v196
	v_exp_f32_e32 v194, v150
	v_exp_f32_e32 v195, v151
	s_waitcnt lgkmcnt(3)
	v_mfma_f32_16x16x32_bf16 v[148:151], v[160:163], v[4:7], v[48:51]
	v_add_f32_e32 v180, v157, v156
	v_add_f32_e32 v181, v145, v144
	v_mfma_f32_16x16x32_bf16 v[160:163], v[160:163], v[40:43], v[52:55]
	ds_read_b128 v[176:179], v196 offset:4096
	s_waitcnt lgkmcnt(3)
	v_mfma_f32_16x16x32_bf16 v[164:167], v[168:171], v[4:7], v[48:51]
	v_exp_f32_e32 v190, v140
	v_exp_f32_e32 v191, v141
	v_add_f32_e32 v206, v158, v180
	v_mfma_f32_16x16x32_bf16 v[168:171], v[168:171], v[40:43], v[52:55]
	v_add_f32_e32 v207, v146, v181
	ds_read_b128 v[180:183], v196 offset:8192
	v_exp_f32_e32 v192, v142
	v_exp_f32_e32 v193, v143
	s_waitcnt lgkmcnt(3)
	v_mfma_f32_16x16x32_bf16 v[140:143], v[172:175], v[4:7], v[48:51]
	v_add_f32_e32 v206, v159, v206
	v_add_f32_e32 v207, v147, v207
	v_mfma_f32_16x16x32_bf16 v[172:175], v[172:175], v[40:43], v[52:55]
	s_add_i32 s9, s4, -1
	s_cmp_ge_u32 s9, s2
	s_cbranch_scc1 .LBB0_963
	s_add_u32 s9, s6, s30
	s_addc_u32 s35, s7, s31
	s_add_u32 s34, s9, 0x180000
	s_addc_u32 s35, s35, 0
	s_add_u32 s36, s10, 0xffffe000
	s_mul_i32 s9, s8, 0x6000
	s_addc_u32 s37, s11, -1
	s_add_i32 s9, s9, 0
	s_add_i32 s48, s9, s77
	s_mov_b32 m0, s48
	s_add_i32 s9, s9, s97
	global_load_lds_dwordx4 v227, s[34:35]
	s_add_i32 m0, s48, 0x400
	s_nop 0
	global_load_lds_dwordx4 v229, s[34:35]
	s_add_i32 m0, s9, 0x4000
	s_nop 0
	global_load_lds_dwordx4 v232, s[36:37]
.LBB0_963:
	s_add_u32 s36, s28, s30
	s_addc_u32 s37, s29, s31
	s_add_u32 s34, s36, 0x100000
	s_addc_u32 s35, s37, 0
	s_lshl_b32 s9, s19, 14
	s_add_i32 s48, s95, s9
	s_mov_b32 m0, s48
	s_nop 0
	global_load_lds_dwordx4 v228, s[34:35]
	s_add_i32 m0, s48, 0x400
	s_nop 0
	global_load_lds_dwordx4 v231, s[34:35]
	ds_read_b128 v[236:239], v196 offset:12288
	s_waitcnt lgkmcnt(3)
	v_mfma_f32_16x16x32_bf16 v[120:123], v[184:187], v[36:39], v[120:123]
	v_exp_f32_e32 v196, v132
	v_exp_f32_e32 v208, v133
	v_add_f32_e32 v206, v152, v206
	v_add_f32_e32 v207, v136, v207
	v_mfma_f32_16x16x32_bf16 v[124:127], v[184:187], v[0:3], v[124:127]
	v_add_u32_e32 v209, s25, v233
	ds_read_b128 v[184:187], v209
	v_exp_f32_e32 v210, v134
	v_exp_f32_e32 v211, v135
	s_waitcnt lgkmcnt(3)
	v_mfma_f32_16x16x32_bf16 v[132:135], v[176:179], v[0:3], v[148:151]
	v_mfma_f32_16x16x32_bf16 v[160:163], v[176:179], v[36:39], v[160:163]
	s_nop 1
	v_add_f32_e32 v148, v153, v206
	v_add_f32_e32 v149, v137, v207
	ds_read_b128 v[176:179], v209 offset:4096
	s_waitcnt lgkmcnt(3)
	v_mfma_f32_16x16x32_bf16 v[164:167], v[180:183], v[0:3], v[164:167]
	v_exp_f32_e32 v212, v128
	v_exp_f32_e32 v213, v129
	v_add_f32_e32 v148, v154, v148
	v_mfma_f32_16x16x32_bf16 v[168:171], v[180:183], v[36:39], v[168:171]
	v_add_f32_e32 v149, v138, v149
	ds_read_b128 v[180:183], v209 offset:8192
	v_exp_f32_e32 v219, v130
	v_exp_f32_e32 v235, v131
	s_waitcnt lgkmcnt(3)
	v_mfma_f32_16x16x32_bf16 v[128:131], v[236:239], v[0:3], v[140:143]
	v_add_f32_e32 v148, v155, v148
	v_add_f32_e32 v149, v139, v149
	v_mfma_f32_16x16x32_bf16 v[140:143], v[236:239], v[36:39], v[172:175]
	s_nop 2
	ds_read_b128 v[172:175], v209 offset:12288
	s_waitcnt lgkmcnt(3)
	v_mfma_f32_16x16x32_bf16 v[120:123], v[184:187], v[28:31], v[120:123]
	v_add_f32_e32 v150, v188, v148
	v_add_f32_e32 v149, v190, v149
	v_mfma_f32_16x16x32_bf16 v[124:127], v[184:187], v[12:15], v[124:127]
	v_cvt_pk_bf16_f32 v148, v156, v157
	v_add_u32_e32 v206, s25, v230
	ds_read_b128 v[184:187], v206
	v_add_f32_e32 v150, v189, v150
	v_add_f32_e32 v151, v191, v149
	s_waitcnt lgkmcnt(3)
	v_mfma_f32_16x16x32_bf16 v[132:135], v[176:179], v[12:15], v[132:135]
	v_cvt_pk_bf16_f32 v149, v158, v159
	v_mfma_f32_16x16x32_bf16 v[156:159], v[176:179], v[28:31], v[160:163]
	ds_read_b128 v[176:179], v206 offset:4096
	s_waitcnt lgkmcnt(3)
	v_mfma_f32_16x16x32_bf16 v[162:165], v[180:183], v[12:15], v[164:167]
	s_nop 0
	v_add_f32_e32 v160, v194, v150
	v_add_f32_e32 v151, v192, v151
	v_mfma_f32_16x16x32_bf16 v[166:169], v[180:183], v[28:31], v[168:171]
	v_cvt_pk_bf16_f32 v150, v152, v153
	ds_read_b128 v[180:183], v206 offset:8192
	s_waitcnt lgkmcnt(3)
	v_mfma_f32_16x16x32_bf16 v[128:131], v[172:175], v[12:15], v[128:131]
	v_add_f32_e32 v160, v195, v160
	v_add_f32_e32 v161, v193, v151
	v_mfma_f32_16x16x32_bf16 v[140:143], v[172:175], v[28:31], v[140:143]
	v_cvt_pk_bf16_f32 v151, v154, v155
	ds_read_b128 v[152:155], v206 offset:12288
	s_waitcnt lgkmcnt(3)
	v_mfma_f32_16x16x32_bf16 v[120:123], v[184:187], v[24:27], v[120:123]
	v_add_f32_e32 v174, v196, v160
	v_add_f32_e32 v161, v212, v161
	v_mfma_f32_16x16x32_bf16 v[124:127], v[184:187], v[8:11], v[124:127]
	v_cvt_pk_bf16_f32 v160, v144, v145
	v_add_u32_e32 v186, s25, v226
	ds_read_b128 v[170:173], v186 offset:16384
	v_add_f32_e32 v184, v208, v174
	v_add_f32_e32 v185, v213, v161
	s_waitcnt lgkmcnt(3)
	v_mfma_f32_16x16x32_bf16 v[132:135], v[176:179], v[8:11], v[132:135]
	v_cvt_pk_bf16_f32 v161, v146, v147
	v_mfma_f32_16x16x32_bf16 v[144:147], v[176:179], v[24:27], v[156:159]
	s_nop 2
	ds_read_b128 v[156:159], v186 offset:18432
	s_waitcnt lgkmcnt(3)
	v_mfma_f32_16x16x32_bf16 v[174:177], v[180:183], v[8:11], v[162:165]
	v_mfma_f32_16x16x32_bf16 v[178:181], v[180:183], v[24:27], v[166:169]
	s_nop 1
	v_add_f32_e32 v163, v210, v184
	v_add_f32_e32 v164, v219, v185
	v_cvt_pk_bf16_f32 v162, v136, v137
	ds_read_b128 v[182:185], v186 offset:20480
	v_add_f32_e32 v206, v211, v163
	v_add_f32_e32 v207, v235, v164
	s_waitcnt lgkmcnt(3)
	v_mfma_f32_16x16x32_bf16 v[128:131], v[152:155], v[8:11], v[128:131]
	v_cvt_pk_bf16_f32 v163, v138, v139
	v_mfma_f32_16x16x32_bf16 v[136:139], v[152:155], v[24:27], v[140:143]
	s_nop 2
	ds_read_b128 v[140:143], v186 offset:22528
	s_waitcnt lgkmcnt(3)
	v_mfma_f32_16x16x32_bf16 v[120:123], v[170:173], v[32:35], v[120:123]
	v_cvt_pk_bf16_f32 v164, v188, v189
	v_mfma_f32_16x16x32_bf16 v[124:127], v[170:173], v[16:19], v[124:127]
	v_add_u32_e32 v152, s25, v224
	ds_read_b128 v[168:171], v152 offset:16384
	s_waitcnt lgkmcnt(3)
	v_mfma_f32_16x16x32_bf16 v[132:135], v[156:159], v[16:19], v[132:135]
	v_cvt_pk_bf16_f32 v165, v194, v195
	v_mfma_f32_16x16x32_bf16 v[186:189], v[156:159], v[32:35], v[144:147]
	ds_read_b128 v[236:239], v152 offset:18432
	s_waitcnt lgkmcnt(3)
	v_mfma_f32_16x16x32_bf16 v[240:243], v[182:185], v[16:19], v[174:177]
	v_cvt_pk_bf16_f32 v166, v196, v208
	v_mfma_f32_16x16x32_bf16 v[176:179], v[182:185], v[32:35], v[178:181]
	s_nop 2
	ds_read_b128 v[180:183], v152 offset:20480
	s_waitcnt lgkmcnt(3)
	v_mfma_f32_16x16x32_bf16 v[128:131], v[140:143], v[16:19], v[128:131]
	v_cvt_pk_bf16_f32 v167, v210, v211
	v_mfma_f32_16x16x32_bf16 v[244:247], v[140:143], v[32:35], v[136:139]
	ds_read_b128 v[248:251], v152 offset:22528
	s_waitcnt lgkmcnt(3)
	v_mfma_f32_16x16x32_bf16 v[152:155], v[168:171], v[20:23], v[124:127]
	v_mfma_f32_16x16x32_bf16 v[144:147], v[168:171], v[44:47], v[120:123]
	v_cvt_pk_bf16_f32 v168, v190, v191
	s_waitcnt lgkmcnt(2)
	v_mfma_f32_16x16x32_bf16 v[156:159], v[236:239], v[20:23], v[132:135]
	v_cvt_pk_bf16_f32 v169, v192, v193
	v_mfma_f32_16x16x32_bf16 v[172:175], v[236:239], v[44:47], v[186:189]
	s_waitcnt lgkmcnt(1)
	v_mfma_f32_16x16x32_bf16 v[140:143], v[180:183], v[20:23], v[240:243]
	v_cvt_pk_bf16_f32 v170, v212, v213
	v_mfma_f32_16x16x32_bf16 v[136:139], v[180:183], v[44:47], v[176:179]
	s_waitcnt lgkmcnt(0)
	v_mfma_f32_16x16x32_bf16 v[132:135], v[248:251], v[20:23], v[128:131]
	v_cvt_pk_bf16_f32 v171, v219, v235
	v_mfma_f32_16x16x32_bf16 v[128:131], v[248:251], v[44:47], v[244:247]
	s_lshl_b32 s34, s8, 14
	s_add_i32 s48, s34, 0
	s_add_i32 s48, s48, 0x12000
	v_add_u32_e32 v196, s48, v222
	v_add_u32_e32 v219, s48, v223
	ds_read_b64_tr_b16 v[120:121], v196
	ds_read_b64_tr_b16 v[122:123], v196 offset:4096
	ds_read_b64_tr_b16 v[124:125], v196 offset:8192
	ds_read_b64_tr_b16 v[126:127], v196 offset:12288
	ds_read_b64_tr_b16 v[176:177], v219
	ds_read_b64_tr_b16 v[178:179], v219 offset:4096
	ds_read_b64_tr_b16 v[182:183], v219 offset:4608
	ds_read_b64_tr_b16 v[180:181], v219 offset:512
	ds_read_b64_tr_b16 v[184:185], v219 offset:8192
	ds_read_b64_tr_b16 v[186:187], v219 offset:12288
	ds_read_b64_tr_b16 v[190:191], v219 offset:12800
	ds_read_b64_tr_b16 v[188:189], v219 offset:8704
	s_waitcnt lgkmcnt(6)
	v_mfma_f32_16x16x32_bf16 v[112:115], v[176:179], v[148:151], v[112:115]
	v_mfma_f32_16x16x32_bf16 v[116:119], v[176:179], v[160:163], v[116:119]
	v_max_f32_e32 v176, v152, v153
	s_waitcnt lgkmcnt(2)
	v_mfma_f32_16x16x32_bf16 v[112:115], v[184:187], v[164:167], v[112:115]
	v_max3_f32 v176, v176, v154, v155
	v_max3_f32 v176, v176, v156, v157
	v_max3_f32 v208, v176, v158, v159
	v_mfma_f32_16x16x32_bf16 v[116:119], v[184:187], v[168:171], v[116:119]
	ds_read_b64_tr_b16 v[192:193], v196 offset:512
	ds_read_b64_tr_b16 v[194:195], v196 offset:4608
	ds_read_b64_tr_b16 v[236:237], v196 offset:8704
	ds_read_b64_tr_b16 v[238:239], v196 offset:12800
	v_mfma_f32_16x16x32_bf16 v[108:111], v[120:123], v[148:151], v[108:111]
	v_mfma_f32_16x16x32_bf16 v[176:179], v[120:123], v[160:163], v[104:107]
	v_mfma_f32_16x16x32_bf16 v[104:107], v[124:127], v[164:167], v[108:111]
	s_nop 5
	v_max3_f32 v108, v208, v140, v141
	v_max3_f32 v108, v108, v142, v143
	v_max3_f32 v108, v108, v132, v133
	v_max3_f32 v120, v108, v134, v135
	v_mfma_f32_16x16x32_bf16 v[108:111], v[124:127], v[168:171], v[176:179]
	ds_read_b64_tr_b16 v[184:185], v219 offset:1024
	ds_read_b64_tr_b16 v[186:187], v219 offset:5120
	s_nop 0
	ds_read_b64_tr_b16 v[176:177], v219 offset:9216
	ds_read_b64_tr_b16 v[178:179], v219 offset:13312
	v_mfma_f32_16x16x32_bf16 v[96:99], v[180:183], v[148:151], v[96:99]
	v_max_f32_e32 v121, v144, v145
	s_waitcnt lgkmcnt(8)
	v_mfma_f32_16x16x32_bf16 v[96:99], v[188:191], v[164:167], v[96:99]
	v_max3_f32 v121, v121, v146, v147
	v_max3_f32 v121, v121, v172, v173
	v_max3_f32 v121, v121, v174, v175
	v_mfma_f32_16x16x32_bf16 v[100:103], v[180:183], v[160:163], v[100:103]
	v_mfma_f32_16x16x32_bf16 v[100:103], v[188:191], v[168:171], v[100:103]
	ds_read_b64_tr_b16 v[188:189], v196 offset:1024
	ds_read_b64_tr_b16 v[190:191], v196 offset:5120
	ds_read_b64_tr_b16 v[180:181], v196 offset:9216
	ds_read_b64_tr_b16 v[182:183], v196 offset:13312
	s_waitcnt lgkmcnt(10)
	v_mfma_f32_16x16x32_bf16 v[92:95], v[192:195], v[148:151], v[92:95]
	v_mfma_f32_16x16x32_bf16 v[122:125], v[192:195], v[160:163], v[88:91]
	s_waitcnt lgkmcnt(8)
	v_mfma_f32_16x16x32_bf16 v[88:91], v[236:239], v[164:167], v[92:95]
	s_nop 5
	v_max3_f32 v92, v121, v136, v137
	v_max3_f32 v92, v92, v138, v139
	v_max3_f32 v92, v92, v128, v129
	v_max3_f32 v121, v92, v130, v131
	v_mfma_f32_16x16x32_bf16 v[92:95], v[236:239], v[168:171], v[122:125]
	s_nop 2
	v_max_f32_e32 v122, v120, v121
	v_cmp_ge_f32_e32 vcc, s62, v122
	s_cmp_lg_u64 vcc, exec
	s_cselect_b64 s[34:35], -1, 0
	s_cmp_eq_u64 vcc, exec
	s_cbranch_scc1 .LBB0_965
	ds_bpermute_b32 v48, v220, v120
	v_max_f32_e32 v49, v120, v120
	v_max_f32_e32 v50, v121, v121
	s_waitcnt lgkmcnt(0)
	v_max_f32_e32 v48, v48, v48
	v_max_f32_e32 v48, v49, v48
	ds_bpermute_b32 v49, v221, v48
	s_waitcnt lgkmcnt(0)
	v_max3_f32 v48, v48, v49, 0
	ds_bpermute_b32 v49, v220, v121
	v_exp_f32_e64 v208, -v48
	v_sub_f32_e32 v152, v152, v48
	v_sub_f32_e32 v153, v153, v48
	v_sub_f32_e32 v154, v154, v48
	s_waitcnt lgkmcnt(0)
	v_max_f32_e32 v49, v49, v49
	v_max_f32_e32 v49, v50, v49
	ds_bpermute_b32 v50, v221, v49
	v_sub_f32_e32 v155, v155, v48
	v_sub_f32_e32 v156, v156, v48
	v_sub_f32_e32 v157, v157, v48
	v_sub_f32_e32 v158, v158, v48
	s_waitcnt lgkmcnt(0)
	v_max3_f32 v49, v49, v50, 0
	v_exp_f32_e64 v209, -v49
	v_pk_add_f32 v[202:203], v[202:203], v[48:49]
	v_sub_f32_e32 v159, v159, v48
	v_pk_add_f32 v[120:121], v[202:203], 0 neg_lo:[1,1] neg_hi:[1,1]
	v_xor_b32_e32 v124, 0x80000000, v203
	v_sub_f32_e32 v143, v143, v48
	v_sub_f32_e32 v142, v142, v48
	v_sub_f32_e32 v141, v141, v48
	v_sub_f32_e32 v140, v140, v48
	v_sub_f32_e32 v135, v135, v48
	v_sub_f32_e32 v134, v134, v48
	v_sub_f32_e32 v133, v133, v48
	v_sub_f32_e32 v132, v132, v48
	v_mov_b32_e32 v121, v120
	v_mov_b32_e32 v122, v120
	v_mov_b32_e32 v123, v120
	v_sub_f32_e32 v144, v144, v49
	v_sub_f32_e32 v145, v145, v49
	v_sub_f32_e32 v146, v146, v49
	v_sub_f32_e32 v147, v147, v49
	v_sub_f32_e32 v172, v172, v49
	v_sub_f32_e32 v173, v173, v49
	v_sub_f32_e32 v174, v174, v49
	v_sub_f32_e32 v175, v175, v49
	v_sub_f32_e32 v139, v139, v49
	v_sub_f32_e32 v138, v138, v49
	v_sub_f32_e32 v137, v137, v49
	v_sub_f32_e32 v136, v136, v49
	v_sub_f32_e32 v131, v131, v49
	v_sub_f32_e32 v130, v130, v49
	v_sub_f32_e32 v129, v129, v49
	v_sub_f32_e32 v128, v128, v49
	v_mov_b32_e32 v125, v124
	v_mov_b32_e32 v126, v124
	v_mov_b32_e32 v127, v124
	v_mov_b32_e32 v48, v120
	v_mov_b32_e32 v49, v120
	v_mov_b32_e32 v50, v120
	v_mov_b32_e32 v51, v120
	v_mov_b32_e32 v52, v124
	v_mov_b32_e32 v53, v124
	v_mov_b32_e32 v54, v124
	v_mov_b32_e32 v55, v124
	s_branch .LBB0_966

.LBB0_966:
	ds_read_b64_tr_b16 v[192:193], v219 offset:1536
	ds_read_b64_tr_b16 v[194:195], v219 offset:5632
	ds_read_b64_tr_b16 v[236:237], v219 offset:9728
	ds_read_b64_tr_b16 v[238:239], v219 offset:13824
	s_waitcnt lgkmcnt(10)
	v_mfma_f32_16x16x32_bf16 v[80:83], v[184:187], v[148:151], v[80:83]
	v_exp_f32_e32 v152, v152
	v_exp_f32_e32 v153, v153
	v_exp_f32_e32 v154, v154
	s_waitcnt lgkmcnt(8)
	v_mfma_f32_16x16x32_bf16 v[80:83], v[176:179], v[164:167], v[80:83]
	v_exp_f32_e32 v155, v155
	v_mfma_f32_16x16x32_bf16 v[84:87], v[184:187], v[160:163], v[84:87]
	v_mfma_f32_16x16x32_bf16 v[84:87], v[176:179], v[168:171], v[84:87]
	ds_read_b64_tr_b16 v[176:177], v196 offset:1536
	ds_read_b64_tr_b16 v[178:179], v196 offset:5632
	ds_read_b64_tr_b16 v[184:185], v196 offset:9728
	ds_read_b64_tr_b16 v[186:187], v196 offset:13824
	s_waitcnt lgkmcnt(10)
	v_mfma_f32_16x16x32_bf16 v[72:75], v[188:191], v[148:151], v[72:75]
	v_exp_f32_e32 v144, v144
	v_exp_f32_e32 v145, v145
	v_exp_f32_e32 v146, v146
	s_waitcnt lgkmcnt(8)
	v_mfma_f32_16x16x32_bf16 v[72:75], v[180:183], v[164:167], v[72:75]
	v_exp_f32_e32 v147, v147
	v_mfma_f32_16x16x32_bf16 v[76:79], v[188:191], v[160:163], v[76:79]
	v_mfma_f32_16x16x32_bf16 v[76:79], v[180:183], v[168:171], v[76:79]
	s_waitcnt lgkmcnt(6)
	v_mfma_f32_16x16x32_bf16 v[64:67], v[192:195], v[148:151], v[64:67]
	v_exp_f32_e32 v156, v156
	v_exp_f32_e32 v157, v157
	v_exp_f32_e32 v158, v158
	s_waitcnt lgkmcnt(4)
	v_mfma_f32_16x16x32_bf16 v[64:67], v[236:239], v[164:167], v[64:67]
	v_exp_f32_e32 v159, v159
	v_mfma_f32_16x16x32_bf16 v[68:71], v[192:195], v[160:163], v[68:71]
	v_mfma_f32_16x16x32_bf16 v[68:71], v[236:239], v[168:171], v[68:71]
	s_waitcnt lgkmcnt(2)
	v_mfma_f32_16x16x32_bf16 v[56:59], v[176:179], v[148:151], v[56:59]
	v_exp_f32_e32 v148, v172
	v_exp_f32_e32 v149, v173
	v_exp_f32_e32 v150, v174
	s_waitcnt lgkmcnt(0)
	v_mfma_f32_16x16x32_bf16 v[56:59], v[184:187], v[164:167], v[56:59]
	v_exp_f32_e32 v151, v175
	s_andn2_b64 vcc, exec, s[34:35]
	v_mfma_f32_16x16x32_bf16 v[60:63], v[176:179], v[160:163], v[60:63]
	v_mfma_f32_16x16x32_bf16 v[60:63], v[184:187], v[168:171], v[60:63]
	s_cbranch_vccnz .LBB0_969
	v_max_f32_e32 v160, v209, v209
	v_max_f32_e32 v161, v208, v208
	v_min_f32_e32 v160, v161, v160
	v_cmp_gt_f32_e32 vcc, 1.0, v160
	s_cbranch_vccz .LBB0_969
	v_pk_mul_f32 v[112:113], v[112:113], v[208:209] op_sel_hi:[1,0]
	v_pk_mul_f32 v[114:115], v[114:115], v[208:209] op_sel_hi:[1,0]
	v_pk_mul_f32 v[104:105], v[104:105], v[208:209] op_sel_hi:[1,0]
	v_pk_mul_f32 v[106:107], v[106:107], v[208:209] op_sel_hi:[1,0]
	v_pk_mul_f32 v[96:97], v[96:97], v[208:209] op_sel_hi:[1,0]
	v_pk_mul_f32 v[98:99], v[98:99], v[208:209] op_sel_hi:[1,0]
	v_pk_mul_f32 v[88:89], v[88:89], v[208:209] op_sel_hi:[1,0]
	v_pk_mul_f32 v[90:91], v[90:91], v[208:209] op_sel_hi:[1,0]
	v_pk_mul_f32 v[80:81], v[208:209], v[80:81] op_sel_hi:[0,1]
	v_pk_mul_f32 v[82:83], v[208:209], v[82:83] op_sel_hi:[0,1]
	v_pk_mul_f32 v[72:73], v[208:209], v[72:73] op_sel_hi:[0,1]
	v_pk_mul_f32 v[74:75], v[208:209], v[74:75] op_sel_hi:[0,1]
	v_pk_mul_f32 v[64:65], v[208:209], v[64:65] op_sel_hi:[0,1]
	v_pk_mul_f32 v[66:67], v[208:209], v[66:67] op_sel_hi:[0,1]
	v_pk_mul_f32 v[56:57], v[208:209], v[56:57] op_sel_hi:[0,1]
	v_pk_mul_f32 v[58:59], v[208:209], v[58:59] op_sel_hi:[0,1]
	v_pk_mul_f32 v[116:117], v[116:117], v[208:209] op_sel:[0,1]
	v_pk_mul_f32 v[118:119], v[118:119], v[208:209] op_sel:[0,1]
	v_pk_mul_f32 v[108:109], v[108:109], v[208:209] op_sel:[0,1]
	v_pk_mul_f32 v[110:111], v[110:111], v[208:209] op_sel:[0,1]
	v_pk_mul_f32 v[100:101], v[100:101], v[208:209] op_sel:[0,1]
	v_pk_mul_f32 v[102:103], v[102:103], v[208:209] op_sel:[0,1]
	v_pk_mul_f32 v[92:93], v[92:93], v[208:209] op_sel:[0,1]
	v_pk_mul_f32 v[94:95], v[94:95], v[208:209] op_sel:[0,1]
	v_pk_mul_f32 v[84:85], v[208:209], v[84:85] op_sel:[1,0]
	v_pk_mul_f32 v[86:87], v[208:209], v[86:87] op_sel:[1,0]
	v_pk_mul_f32 v[76:77], v[208:209], v[76:77] op_sel:[1,0]
	v_pk_mul_f32 v[78:79], v[208:209], v[78:79] op_sel:[1,0]
	v_pk_mul_f32 v[68:69], v[208:209], v[68:69] op_sel:[1,0]
	v_pk_mul_f32 v[70:71], v[208:209], v[70:71] op_sel:[1,0]
	v_pk_mul_f32 v[60:61], v[208:209], v[60:61] op_sel:[1,0]
	v_pk_mul_f32 v[62:63], v[208:209], v[62:63] op_sel:[1,0]
.LBB0_969:
	s_waitcnt vmcnt(5)
	s_barrier
	s_mul_i32 s34, s19, 0x6000
	s_add_i32 s49, s34, 0
	v_add_u32_e32 v164, s49, v225
	ds_read_b128 v[160:163], v164
	ds_read_b128 v[168:171], v164 offset:4096
	ds_read_b128 v[184:187], v164 offset:8192
	ds_read_b128 v[246:249], v164 offset:12288
	s_waitcnt lgkmcnt(3)
	v_mfma_f32_16x16x32_bf16 v[164:167], v[160:163], v[4:7], v[120:123]
	v_exp_f32_e32 v235, v140
	v_exp_f32_e32 v236, v141
	v_mfma_f32_16x16x32_bf16 v[160:163], v[160:163], v[40:43], v[124:127]
	v_add_u32_e32 v243, s49, v234
	ds_read_b128 v[192:195], v243
	s_waitcnt lgkmcnt(3)
	v_mfma_f32_16x16x32_bf16 v[180:183], v[168:171], v[4:7], v[120:123]
	v_exp_f32_e32 v241, v142
	v_exp_f32_e32 v242, v143
	v_add_f32_e32 v140, v153, v152
	v_mfma_f32_16x16x32_bf16 v[172:175], v[168:171], v[40:43], v[124:127]
	v_add_f32_e32 v141, v145, v144
	ds_read_b128 v[188:191], v243 offset:4096
	v_exp_f32_e32 v237, v136
	v_exp_f32_e32 v238, v137
	s_waitcnt lgkmcnt(3)
	v_mfma_f32_16x16x32_bf16 v[176:179], v[184:187], v[4:7], v[120:123]
	v_add_f32_e32 v136, v154, v140
	v_add_f32_e32 v137, v146, v141
	v_mfma_f32_16x16x32_bf16 v[140:143], v[184:187], v[40:43], v[124:127]
	ds_read_b128 v[184:187], v243 offset:8192
	v_exp_f32_e32 v239, v138
	v_exp_f32_e32 v240, v139
	s_waitcnt lgkmcnt(3)
	v_mfma_f32_16x16x32_bf16 v[168:171], v[246:249], v[4:7], v[120:123]
	v_add_f32_e32 v245, v155, v136
	v_add_f32_e32 v244, v147, v137
	v_mfma_f32_16x16x32_bf16 v[136:139], v[246:249], v[40:43], v[124:127]
	s_cmp_ge_u32 s4, s2
	s_cselect_b64 s[34:35], -1, 0
	s_and_b64 vcc, exec, s[34:35]
	s_cbranch_vccnz .LBB0_971
	s_add_u32 s65, s6, s30
	s_addc_u32 s69, s7, s31
	s_add_u32 s70, s65, 0x200000
	s_addc_u32 s71, s69, 0
	s_add_i32 s65, s25, s77
	s_mov_b64 s[80:81], s[10:11]
	s_mov_b32 m0, s65
	s_add_i32 s25, s25, s97
	global_load_lds_dwordx4 v227, s[70:71]
	s_add_i32 m0, s65, 0x400
	s_nop 0
	global_load_lds_dwordx4 v229, s[70:71]
	s_add_i32 m0, s25, 0x4000
	s_nop 0
	global_load_lds_dwordx4 v232, s[80:81]
.LBB0_971:
	s_add_u32 s36, s36, 0x180000
	s_addc_u32 s37, s37, 0
	s_add_i32 s25, s48, s77
	s_mov_b32 m0, s25
	s_nop 0
	global_load_lds_dwordx4 v228, s[36:37]
	s_add_i32 m0, s25, 0x400
	s_nop 0
	global_load_lds_dwordx4 v231, s[36:37]
	ds_read_b128 v[246:249], v243 offset:12288
	s_waitcnt lgkmcnt(3)
	v_mfma_f32_16x16x32_bf16 v[164:167], v[192:195], v[0:3], v[164:167]
	v_exp_f32_e32 v210, v132
	v_exp_f32_e32 v211, v133
	v_add_f32_e32 v212, v156, v245
	v_mfma_f32_16x16x32_bf16 v[160:163], v[192:195], v[36:39], v[160:163]
	v_add_f32_e32 v213, v148, v244
	v_add_u32_e32 v243, s49, v233
	ds_read_b128 v[192:195], v243
	v_exp_f32_e32 v250, v134
	v_exp_f32_e32 v251, v135
	s_waitcnt lgkmcnt(3)
	v_mfma_f32_16x16x32_bf16 v[132:135], v[188:191], v[0:3], v[180:183]
	v_add_f32_e32 v212, v157, v212
	v_add_f32_e32 v213, v149, v213
	v_mfma_f32_16x16x32_bf16 v[172:175], v[188:191], v[36:39], v[172:175]
	ds_read_b128 v[180:183], v243 offset:4096
	s_waitcnt lgkmcnt(3)
	v_mfma_f32_16x16x32_bf16 v[176:179], v[184:187], v[0:3], v[176:179]
	v_exp_f32_e32 v215, v128
	v_exp_f32_e32 v214, v129
	v_add_f32_e32 v188, v158, v212
	v_mfma_f32_16x16x32_bf16 v[140:143], v[184:187], v[36:39], v[140:143]
	v_add_f32_e32 v189, v150, v213
	ds_read_b128 v[184:187], v243 offset:8192
	v_exp_f32_e32 v218, v130
	v_exp_f32_e32 v198, v131
	s_waitcnt lgkmcnt(3)
	v_mfma_f32_16x16x32_bf16 v[128:131], v[246:249], v[0:3], v[168:171]
	v_add_f32_e32 v199, v159, v188
	v_add_f32_e32 v212, v151, v189
	v_mfma_f32_16x16x32_bf16 v[168:171], v[246:249], v[36:39], v[136:139]
	ds_read_b128 v[188:191], v243 offset:12288
	s_waitcnt lgkmcnt(3)
	v_mfma_f32_16x16x32_bf16 v[164:167], v[192:195], v[12:15], v[164:167]
	v_add_f32_e32 v137, v235, v199
	v_add_f32_e32 v138, v237, v212
	v_mfma_f32_16x16x32_bf16 v[160:163], v[192:195], v[28:31], v[160:163]
	v_cvt_pk_bf16_f32 v136, v152, v153
	v_add_u32_e32 v199, s49, v230
	ds_read_b128 v[192:195], v199
	v_add_f32_e32 v139, v236, v137
	v_add_f32_e32 v138, v238, v138
	s_waitcnt lgkmcnt(3)
	v_mfma_f32_16x16x32_bf16 v[132:135], v[180:183], v[12:15], v[132:135]
	v_cvt_pk_bf16_f32 v137, v154, v155
	v_mfma_f32_16x16x32_bf16 v[152:155], v[180:183], v[28:31], v[172:175]
	s_nop 2
	ds_read_b128 v[172:175], v199 offset:4096
	s_waitcnt lgkmcnt(3)
	v_mfma_f32_16x16x32_bf16 v[176:179], v[184:187], v[12:15], v[176:179]
	v_add_f32_e32 v139, v241, v139
	v_add_f32_e32 v212, v239, v138
	v_mfma_f32_16x16x32_bf16 v[140:143], v[184:187], v[28:31], v[140:143]
	v_cvt_pk_bf16_f32 v138, v156, v157
	ds_read_b128 v[180:183], v199 offset:8192
	v_add_f32_e32 v213, v242, v139
	v_add_f32_e32 v212, v240, v212
	s_waitcnt lgkmcnt(3)
	v_mfma_f32_16x16x32_bf16 v[128:131], v[188:191], v[12:15], v[128:131]
	v_cvt_pk_bf16_f32 v139, v158, v159
	v_mfma_f32_16x16x32_bf16 v[156:159], v[188:191], v[28:31], v[168:171]
	s_nop 2
	ds_read_b128 v[168:171], v199 offset:12288
	s_waitcnt lgkmcnt(3)
	v_mfma_f32_16x16x32_bf16 v[164:167], v[192:195], v[8:11], v[164:167]
	v_mfma_f32_16x16x32_bf16 v[184:187], v[192:195], v[24:27], v[160:163]
	s_nop 2
	v_add_f32_e32 v161, v210, v213
	v_add_f32_e32 v162, v215, v212
	v_cvt_pk_bf16_f32 v160, v144, v145
	v_add_u32_e32 v192, s49, v226
	ds_read_b128 v[188:191], v192 offset:16384
	v_add_f32_e32 v163, v211, v161
	v_add_f32_e32 v162, v214, v162
	s_waitcnt lgkmcnt(3)
	v_mfma_f32_16x16x32_bf16 v[132:135], v[172:175], v[8:11], v[132:135]
	v_cvt_pk_bf16_f32 v161, v146, v147
	v_mfma_f32_16x16x32_bf16 v[144:147], v[172:175], v[24:27], v[152:155]
	s_nop 2
	ds_read_b128 v[152:155], v192 offset:18432
	s_waitcnt lgkmcnt(3)
	v_mfma_f32_16x16x32_bf16 v[172:175], v[180:183], v[8:11], v[176:179]
	v_add_f32_e32 v163, v250, v163
	v_add_f32_e32 v193, v218, v162
	v_mfma_f32_16x16x32_bf16 v[140:143], v[180:183], v[24:27], v[140:143]
	v_cvt_pk_bf16_f32 v162, v148, v149
	ds_read_b128 v[176:179], v192 offset:20480
	v_add_f32_e32 v194, v251, v163
	v_add_f32_e32 v195, v198, v193
	s_waitcnt lgkmcnt(3)
	v_mfma_f32_16x16x32_bf16 v[128:131], v[168:171], v[8:11], v[128:131]
	v_cvt_pk_bf16_f32 v163, v150, v151
	v_mfma_f32_16x16x32_bf16 v[148:151], v[168:171], v[24:27], v[156:159]
	s_nop 2
	ds_read_b128 v[156:159], v192 offset:22528
	s_waitcnt lgkmcnt(3)
	v_mfma_f32_16x16x32_bf16 v[168:171], v[188:191], v[16:19], v[164:167]
	v_cvt_pk_bf16_f32 v164, v235, v236
	v_mfma_f32_16x16x32_bf16 v[180:183], v[188:191], v[32:35], v[184:187]
	v_add_u32_e32 v192, s49, v224
	s_nop 1
	ds_read_b128 v[184:187], v192 offset:16384
	s_waitcnt lgkmcnt(3)
	v_mfma_f32_16x16x32_bf16 v[132:135], v[152:155], v[16:19], v[132:135]
	v_cvt_pk_bf16_f32 v165, v241, v242
	v_mfma_f32_16x16x32_bf16 v[188:191], v[152:155], v[32:35], v[144:147]
	ds_read_b128 v[242:245], v192 offset:18432
	s_waitcnt lgkmcnt(3)
	v_mfma_f32_16x16x32_bf16 v[140:143], v[176:179], v[32:35], v[140:143]
	v_cvt_pk_bf16_f32 v166, v210, v211
	v_mfma_f32_16x16x32_bf16 v[246:249], v[176:179], v[16:19], v[172:175]
	ds_read_b128 v[176:179], v192 offset:20480
	s_waitcnt lgkmcnt(3)
	v_mfma_f32_16x16x32_bf16 v[128:131], v[156:159], v[16:19], v[128:131]
	v_cvt_pk_bf16_f32 v167, v250, v251
	v_mfma_f32_16x16x32_bf16 v[250:253], v[156:159], v[32:35], v[148:151]
	ds_read_b128 v[210:213], v192 offset:22528
	s_waitcnt lgkmcnt(3)
	v_mfma_f32_16x16x32_bf16 v[156:159], v[184:187], v[20:23], v[168:171]
	v_cvt_pk_bf16_f32 v168, v237, v238
	v_mfma_f32_16x16x32_bf16 v[144:147], v[184:187], v[44:47], v[180:183]
	s_waitcnt lgkmcnt(2)
	v_mfma_f32_16x16x32_bf16 v[152:155], v[242:245], v[20:23], v[132:135]
	v_cvt_pk_bf16_f32 v169, v239, v240
	v_mfma_f32_16x16x32_bf16 v[172:175], v[242:245], v[44:47], v[188:191]
	s_waitcnt lgkmcnt(1)
	v_mfma_f32_16x16x32_bf16 v[148:151], v[176:179], v[20:23], v[246:249]
	v_cvt_pk_bf16_f32 v170, v215, v214
	v_mfma_f32_16x16x32_bf16 v[140:143], v[176:179], v[44:47], v[140:143]
	s_waitcnt lgkmcnt(0)
	v_mfma_f32_16x16x32_bf16 v[132:135], v[210:213], v[20:23], v[128:131]
	v_cvt_pk_bf16_f32 v171, v218, v198
	v_mfma_f32_16x16x32_bf16 v[128:131], v[210:213], v[44:47], v[250:253]
	s_lshl_b32 s25, s5, 14
	s_add_i32 s25, s25, 0
	s_add_i32 s25, s25, 0x12000
	v_add_u32_e32 v235, s25, v222
	v_add_u32_e32 v236, s25, v223
	ds_read_b64_tr_b16 v[176:177], v235
	ds_read_b64_tr_b16 v[178:179], v235 offset:4096
	ds_read_b64_tr_b16 v[180:181], v235 offset:8192
	ds_read_b64_tr_b16 v[182:183], v235 offset:12288
	ds_read_b64_tr_b16 v[184:185], v236
	ds_read_b64_tr_b16 v[186:187], v236 offset:4096
	ds_read_b64_tr_b16 v[190:191], v236 offset:4608
	ds_read_b64_tr_b16 v[188:189], v236 offset:512
	ds_read_b64_tr_b16 v[210:211], v236 offset:8192
	ds_read_b64_tr_b16 v[212:213], v236 offset:12288
	ds_read_b64_tr_b16 v[240:241], v236 offset:12800
	ds_read_b64_tr_b16 v[238:239], v236 offset:8704
	s_waitcnt lgkmcnt(6)
	v_mfma_f32_16x16x32_bf16 v[112:115], v[184:187], v[136:139], v[112:115]
	v_mfma_f32_16x16x32_bf16 v[116:119], v[184:187], v[160:163], v[116:119]
	v_max_f32_e32 v184, v156, v157
	s_waitcnt lgkmcnt(2)
	v_mfma_f32_16x16x32_bf16 v[112:115], v[210:213], v[164:167], v[112:115]
	v_max3_f32 v184, v184, v158, v159
	v_max3_f32 v184, v184, v152, v153
	v_max3_f32 v184, v184, v154, v155
	v_mfma_f32_16x16x32_bf16 v[116:119], v[210:213], v[168:171], v[116:119]
	ds_read_b64_tr_b16 v[210:211], v235 offset:512
	ds_read_b64_tr_b16 v[212:213], v235 offset:4608
	ds_read_b64_tr_b16 v[242:243], v235 offset:8704
	ds_read_b64_tr_b16 v[244:245], v235 offset:12800
	v_mfma_f32_16x16x32_bf16 v[104:107], v[176:179], v[136:139], v[104:107]
	v_mfma_f32_16x16x32_bf16 v[176:179], v[176:179], v[160:163], v[108:111]
	v_mfma_f32_16x16x32_bf16 v[108:111], v[180:183], v[164:167], v[104:107]
	s_nop 5
	v_max3_f32 v104, v184, v148, v149
	v_max3_f32 v104, v104, v150, v151
	v_max3_f32 v104, v104, v132, v133
	v_max3_f32 v193, v104, v134, v135
	v_mfma_f32_16x16x32_bf16 v[104:107], v[180:183], v[168:171], v[176:179]
	ds_read_b64_tr_b16 v[184:185], v236 offset:1024
	ds_read_b64_tr_b16 v[186:187], v236 offset:5120
	s_nop 0
	ds_read_b64_tr_b16 v[176:177], v236 offset:9216
	ds_read_b64_tr_b16 v[178:179], v236 offset:13312
	v_mfma_f32_16x16x32_bf16 v[96:99], v[188:191], v[136:139], v[96:99]
	v_max_f32_e32 v180, v144, v145
	s_waitcnt lgkmcnt(8)
	v_mfma_f32_16x16x32_bf16 v[96:99], v[238:241], v[164:167], v[96:99]
	v_max3_f32 v180, v180, v146, v147
	v_max3_f32 v180, v180, v172, v173
	v_max3_f32 v192, v180, v174, v175
	v_mfma_f32_16x16x32_bf16 v[100:103], v[188:191], v[160:163], v[100:103]
	v_mfma_f32_16x16x32_bf16 v[100:103], v[238:241], v[168:171], v[100:103]
	ds_read_b64_tr_b16 v[188:189], v235 offset:1024
	ds_read_b64_tr_b16 v[190:191], v235 offset:5120
	ds_read_b64_tr_b16 v[180:181], v235 offset:9216
	ds_read_b64_tr_b16 v[182:183], v235 offset:13312
	s_waitcnt lgkmcnt(10)
	v_mfma_f32_16x16x32_bf16 v[88:91], v[210:213], v[136:139], v[88:91]
	v_mfma_f32_16x16x32_bf16 v[210:213], v[210:213], v[160:163], v[92:95]
	s_waitcnt lgkmcnt(8)
	v_mfma_f32_16x16x32_bf16 v[92:95], v[242:245], v[164:167], v[88:91]
	s_nop 5
	v_max3_f32 v88, v192, v140, v141
	v_max3_f32 v88, v88, v142, v143
	v_max3_f32 v88, v88, v128, v129
	v_max3_f32 v237, v88, v130, v131
	v_mfma_f32_16x16x32_bf16 v[88:91], v[242:245], v[168:171], v[210:213]
	v_max_f32_e32 v192, v193, v237
	v_cmp_ge_f32_e32 vcc, s62, v192
	s_cmp_lg_u64 vcc, exec
	s_cselect_b64 s[36:37], -1, 0
	s_cmp_eq_u64 vcc, exec
	v_mov_b32_e32 v192, 1.0
	s_cbranch_scc1 .LBB0_973
	ds_bpermute_b32 v48, v220, v193
	v_max_f32_e32 v49, v193, v193
	v_max_f32_e32 v50, v237, v237
	s_waitcnt lgkmcnt(0)
	v_max_f32_e32 v48, v48, v48
	v_max_f32_e32 v48, v49, v48
	ds_bpermute_b32 v49, v221, v48
	s_waitcnt lgkmcnt(0)
	v_max3_f32 v48, v48, v49, 0
	ds_bpermute_b32 v49, v220, v237
	v_exp_f32_e64 v192, -v48
	v_sub_f32_e32 v156, v156, v48
	v_sub_f32_e32 v157, v157, v48
	v_sub_f32_e32 v158, v158, v48
	s_waitcnt lgkmcnt(0)
	v_max_f32_e32 v49, v49, v49
	v_max_f32_e32 v49, v50, v49
	ds_bpermute_b32 v50, v221, v49
	v_sub_f32_e32 v159, v159, v48
	v_sub_f32_e32 v152, v152, v48
	v_sub_f32_e32 v153, v153, v48
	v_sub_f32_e32 v154, v154, v48
	s_waitcnt lgkmcnt(0)
	v_max3_f32 v49, v49, v50, 0
	v_exp_f32_e64 v193, -v49
	v_pk_add_f32 v[202:203], v[202:203], v[48:49]
	v_sub_f32_e32 v155, v155, v48
	v_pk_add_f32 v[120:121], v[202:203], 0 neg_lo:[1,1] neg_hi:[1,1]
	v_xor_b32_e32 v124, 0x80000000, v203
	v_sub_f32_e32 v151, v151, v48
	v_sub_f32_e32 v150, v150, v48
	v_sub_f32_e32 v149, v149, v48
	v_sub_f32_e32 v148, v148, v48
	v_sub_f32_e32 v135, v135, v48
	v_sub_f32_e32 v134, v134, v48
	v_sub_f32_e32 v133, v133, v48
	v_sub_f32_e32 v132, v132, v48
	v_mov_b32_e32 v121, v120
	v_mov_b32_e32 v122, v120
	v_mov_b32_e32 v123, v120
	v_sub_f32_e32 v144, v144, v49
	v_sub_f32_e32 v145, v145, v49
	v_sub_f32_e32 v146, v146, v49
	v_sub_f32_e32 v147, v147, v49
	v_sub_f32_e32 v172, v172, v49
	v_sub_f32_e32 v173, v173, v49
	v_sub_f32_e32 v174, v174, v49
	v_sub_f32_e32 v175, v175, v49
	v_sub_f32_e32 v143, v143, v49
	v_sub_f32_e32 v142, v142, v49
	v_sub_f32_e32 v141, v141, v49
	v_sub_f32_e32 v140, v140, v49
	v_sub_f32_e32 v131, v131, v49
	v_sub_f32_e32 v130, v130, v49
	v_sub_f32_e32 v129, v129, v49
	v_sub_f32_e32 v128, v128, v49
	v_mov_b32_e32 v125, v124
	v_mov_b32_e32 v126, v124
	v_mov_b32_e32 v127, v124
	v_mov_b32_e32 v48, v120
	v_mov_b32_e32 v49, v120
	v_mov_b32_e32 v50, v120
	v_mov_b32_e32 v51, v120
	v_mov_b32_e32 v52, v124
	v_mov_b32_e32 v53, v124
	v_mov_b32_e32 v54, v124
	v_mov_b32_e32 v55, v124
	s_branch .LBB0_974

.LBB0_974:
	ds_read_b64_tr_b16 v[210:211], v236 offset:1536
	ds_read_b64_tr_b16 v[212:213], v236 offset:5632
	ds_read_b64_tr_b16 v[238:239], v236 offset:9728
	ds_read_b64_tr_b16 v[240:241], v236 offset:13824
	s_waitcnt lgkmcnt(10)
	v_mfma_f32_16x16x32_bf16 v[80:83], v[184:187], v[136:139], v[80:83]
	v_exp_f32_e32 v156, v156
	v_exp_f32_e32 v157, v157
	v_exp_f32_e32 v158, v158
	s_waitcnt lgkmcnt(8)
	v_mfma_f32_16x16x32_bf16 v[80:83], v[176:179], v[164:167], v[80:83]
	v_exp_f32_e32 v159, v159
	v_mfma_f32_16x16x32_bf16 v[84:87], v[184:187], v[160:163], v[84:87]
	v_mfma_f32_16x16x32_bf16 v[84:87], v[176:179], v[168:171], v[84:87]
	ds_read_b64_tr_b16 v[176:177], v235 offset:1536
	ds_read_b64_tr_b16 v[178:179], v235 offset:5632
	ds_read_b64_tr_b16 v[184:185], v235 offset:9728
	ds_read_b64_tr_b16 v[186:187], v235 offset:13824
	s_waitcnt lgkmcnt(10)
	v_mfma_f32_16x16x32_bf16 v[72:75], v[188:191], v[136:139], v[72:75]
	v_exp_f32_e32 v144, v144
	v_exp_f32_e32 v145, v145
	v_exp_f32_e32 v146, v146
	s_waitcnt lgkmcnt(8)
	v_mfma_f32_16x16x32_bf16 v[72:75], v[180:183], v[164:167], v[72:75]
	v_exp_f32_e32 v147, v147
	v_mfma_f32_16x16x32_bf16 v[76:79], v[188:191], v[160:163], v[76:79]
	v_mfma_f32_16x16x32_bf16 v[76:79], v[180:183], v[168:171], v[76:79]
	s_waitcnt lgkmcnt(6)
	v_mfma_f32_16x16x32_bf16 v[64:67], v[210:213], v[136:139], v[64:67]
	v_exp_f32_e32 v152, v152
	v_exp_f32_e32 v153, v153
	v_exp_f32_e32 v154, v154
	s_waitcnt lgkmcnt(4)
	v_mfma_f32_16x16x32_bf16 v[64:67], v[238:241], v[164:167], v[64:67]
	v_exp_f32_e32 v155, v155
	v_mfma_f32_16x16x32_bf16 v[68:71], v[210:213], v[160:163], v[68:71]
	v_mfma_f32_16x16x32_bf16 v[68:71], v[238:241], v[168:171], v[68:71]
	s_waitcnt lgkmcnt(2)
	v_mfma_f32_16x16x32_bf16 v[56:59], v[176:179], v[136:139], v[56:59]
	v_exp_f32_e32 v136, v172
	v_exp_f32_e32 v137, v173
	v_exp_f32_e32 v138, v174
	s_waitcnt lgkmcnt(0)
	v_mfma_f32_16x16x32_bf16 v[56:59], v[184:187], v[164:167], v[56:59]
	v_exp_f32_e32 v139, v175
	s_andn2_b64 vcc, exec, s[36:37]
	v_mfma_f32_16x16x32_bf16 v[60:63], v[176:179], v[160:163], v[60:63]
	v_mfma_f32_16x16x32_bf16 v[60:63], v[184:187], v[168:171], v[60:63]
	s_cbranch_vccnz .LBB0_977
	v_max_f32_e32 v160, v193, v193
	v_max_f32_e32 v161, v192, v192
	v_min_f32_e32 v160, v161, v160
	v_cmp_gt_f32_e32 vcc, 1.0, v160
	s_cbranch_vccz .LBB0_977
	v_pk_mul_f32 v[112:113], v[112:113], v[192:193] op_sel_hi:[1,0]
	v_pk_mul_f32 v[114:115], v[114:115], v[192:193] op_sel_hi:[1,0]
	v_pk_mul_f32 v[108:109], v[108:109], v[192:193] op_sel_hi:[1,0]
	v_pk_mul_f32 v[110:111], v[110:111], v[192:193] op_sel_hi:[1,0]
	v_pk_mul_f32 v[96:97], v[96:97], v[192:193] op_sel_hi:[1,0]
	v_pk_mul_f32 v[98:99], v[98:99], v[192:193] op_sel_hi:[1,0]
	v_pk_mul_f32 v[92:93], v[92:93], v[192:193] op_sel_hi:[1,0]
	v_pk_mul_f32 v[94:95], v[94:95], v[192:193] op_sel_hi:[1,0]
	v_pk_mul_f32 v[80:81], v[192:193], v[80:81] op_sel_hi:[0,1]
	v_pk_mul_f32 v[82:83], v[192:193], v[82:83] op_sel_hi:[0,1]
	v_pk_mul_f32 v[72:73], v[192:193], v[72:73] op_sel_hi:[0,1]
	v_pk_mul_f32 v[74:75], v[192:193], v[74:75] op_sel_hi:[0,1]
	v_pk_mul_f32 v[64:65], v[192:193], v[64:65] op_sel_hi:[0,1]
	v_pk_mul_f32 v[66:67], v[192:193], v[66:67] op_sel_hi:[0,1]
	v_pk_mul_f32 v[56:57], v[192:193], v[56:57] op_sel_hi:[0,1]
	v_pk_mul_f32 v[58:59], v[192:193], v[58:59] op_sel_hi:[0,1]
	v_pk_mul_f32 v[116:117], v[116:117], v[192:193] op_sel:[0,1]
	v_pk_mul_f32 v[118:119], v[118:119], v[192:193] op_sel:[0,1]
	v_pk_mul_f32 v[104:105], v[104:105], v[192:193] op_sel:[0,1]
	v_pk_mul_f32 v[106:107], v[106:107], v[192:193] op_sel:[0,1]
	v_pk_mul_f32 v[100:101], v[100:101], v[192:193] op_sel:[0,1]
	v_pk_mul_f32 v[102:103], v[102:103], v[192:193] op_sel:[0,1]
	v_pk_mul_f32 v[88:89], v[88:89], v[192:193] op_sel:[0,1]
	v_pk_mul_f32 v[90:91], v[90:91], v[192:193] op_sel:[0,1]
	v_pk_mul_f32 v[84:85], v[192:193], v[84:85] op_sel:[1,0]
	v_pk_mul_f32 v[86:87], v[192:193], v[86:87] op_sel:[1,0]
	v_pk_mul_f32 v[76:77], v[192:193], v[76:77] op_sel:[1,0]
	v_pk_mul_f32 v[78:79], v[192:193], v[78:79] op_sel:[1,0]
	v_pk_mul_f32 v[68:69], v[192:193], v[68:69] op_sel:[1,0]
	v_pk_mul_f32 v[70:71], v[192:193], v[70:71] op_sel:[1,0]
	v_pk_mul_f32 v[60:61], v[192:193], v[60:61] op_sel:[1,0]
	v_pk_mul_f32 v[62:63], v[192:193], v[62:63] op_sel:[1,0]

.LBB0_979:
	s_waitcnt vmcnt(2)
	s_barrier
	s_mul_i32 s2, s8, 0x6000
	s_add_i32 s2, s2, 0
	v_add_u32_e32 v164, s2, v225
	ds_read_b128 v[48:51], v164
	ds_read_b128 v[52:55], v164 offset:4096
	ds_read_b128 v[160:163], v164 offset:8192
	ds_read_b128 v[164:167], v164 offset:12288
	s_waitcnt lgkmcnt(3)
	v_mfma_f32_16x16x32_bf16 v[168:171], v[48:51], v[4:7], v[120:123]
	v_exp_f32_e32 v188, v148
	v_exp_f32_e32 v189, v149
	v_add_f32_e32 v176, 0, v156
	v_mfma_f32_16x16x32_bf16 v[48:51], v[48:51], v[40:43], v[124:127]
	v_add_f32_e32 v177, 0, v144
	v_add_u32_e32 v190, s2, v234
	ds_read_b128 v[172:175], v190
	v_exp_f32_e32 v191, v150
	v_exp_f32_e32 v194, v151
	s_waitcnt lgkmcnt(3)
	v_mfma_f32_16x16x32_bf16 v[148:151], v[52:55], v[4:7], v[120:123]
	v_add_f32_e32 v184, v157, v176
	v_add_f32_e32 v185, v145, v177
	v_mfma_f32_16x16x32_bf16 v[52:55], v[52:55], v[40:43], v[124:127]
	ds_read_b128 v[176:179], v190 offset:4096
	v_exp_f32_e32 v195, v140
	v_exp_f32_e32 v202, v141
	v_add_f32_e32 v140, v158, v184
	v_add_f32_e32 v141, v146, v185
	s_waitcnt lgkmcnt(3)
	v_mfma_f32_16x16x32_bf16 v[180:183], v[160:163], v[4:7], v[120:123]
	v_mfma_f32_16x16x32_bf16 v[160:163], v[160:163], v[40:43], v[124:127]
	ds_read_b128 v[184:187], v190 offset:8192
	s_waitcnt lgkmcnt(3)
	v_mfma_f32_16x16x32_bf16 v[4:7], v[164:167], v[4:7], v[120:123]
	v_exp_f32_e32 v203, v142
	v_exp_f32_e32 v204, v143
	v_add_f32_e32 v140, v159, v140
	v_mfma_f32_16x16x32_bf16 v[40:43], v[164:167], v[40:43], v[124:127]
	v_add_f32_e32 v141, v147, v141
	ds_read_b128 v[120:123], v190 offset:12288
	s_waitcnt lgkmcnt(3)
	v_mfma_f32_16x16x32_bf16 v[124:127], v[172:175], v[0:3], v[168:171]
	v_exp_f32_e32 v190, v132
	v_exp_f32_e32 v205, v133
	v_add_f32_e32 v164, v152, v140
	v_mfma_f32_16x16x32_bf16 v[48:51], v[172:175], v[36:39], v[48:51]
	v_add_f32_e32 v165, v136, v141
	v_add_u32_e32 v206, s2, v233
	ds_read_b128 v[140:143], v206
	v_exp_f32_e32 v207, v134
	v_exp_f32_e32 v208, v135
	s_waitcnt lgkmcnt(3)
	v_mfma_f32_16x16x32_bf16 v[132:135], v[176:179], v[0:3], v[148:151]
	v_add_f32_e32 v172, v153, v164
	v_add_f32_e32 v173, v137, v165
	v_mfma_f32_16x16x32_bf16 v[148:151], v[176:179], v[36:39], v[52:55]
	ds_read_b128 v[164:167], v206 offset:4096
	v_exp_f32_e32 v176, v128
	v_exp_f32_e32 v177, v129
	v_add_f32_e32 v52, v154, v172
	v_add_f32_e32 v53, v138, v173
	s_waitcnt lgkmcnt(3)
	v_mfma_f32_16x16x32_bf16 v[168:171], v[184:187], v[0:3], v[180:183]
	v_mfma_f32_16x16x32_bf16 v[160:163], v[184:187], v[36:39], v[160:163]
	ds_read_b128 v[172:175], v206 offset:8192
	s_waitcnt lgkmcnt(3)
	v_mfma_f32_16x16x32_bf16 v[0:3], v[120:123], v[0:3], v[4:7]
	v_exp_f32_e32 v178, v130
	v_exp_f32_e32 v179, v131
	v_add_f32_e32 v52, v155, v52
	v_mfma_f32_16x16x32_bf16 v[4:7], v[120:123], v[36:39], v[40:43]
	v_add_f32_e32 v53, v139, v53
	ds_read_b128 v[36:39], v206 offset:12288
	s_waitcnt lgkmcnt(3)
	v_mfma_f32_16x16x32_bf16 v[40:43], v[140:143], v[12:15], v[124:127]
	v_add_f32_e32 v54, v188, v52
	v_add_f32_e32 v53, v195, v53
	v_mfma_f32_16x16x32_bf16 v[48:51], v[140:143], v[28:31], v[48:51]
	v_cvt_pk_bf16_f32 v52, v156, v157
	v_add_u32_e32 v180, s2, v230
	ds_read_b128 v[120:123], v180
	s_waitcnt lgkmcnt(3)
	v_mfma_f32_16x16x32_bf16 v[124:127], v[164:167], v[12:15], v[132:135]
	v_add_f32_e32 v54, v189, v54
	v_add_f32_e32 v55, v202, v53
	v_mfma_f32_16x16x32_bf16 v[128:131], v[164:167], v[28:31], v[148:151]
	v_cvt_pk_bf16_f32 v53, v158, v159
	ds_read_b128 v[132:135], v180 offset:4096
	s_waitcnt lgkmcnt(3)
	v_mfma_f32_16x16x32_bf16 v[140:143], v[172:175], v[12:15], v[168:171]
	v_add_f32_e32 v164, v191, v54
	v_add_f32_e32 v55, v203, v55
	v_cvt_pk_bf16_f32 v54, v152, v153
	v_mfma_f32_16x16x32_bf16 v[148:151], v[172:175], v[28:31], v[160:163]
	ds_read_b128 v[156:159], v180 offset:8192
	s_waitcnt lgkmcnt(3)
	v_mfma_f32_16x16x32_bf16 v[0:3], v[36:39], v[12:15], v[0:3]
	v_add_f32_e32 v152, v194, v164
	v_add_f32_e32 v153, v204, v55
	v_mfma_f32_16x16x32_bf16 v[4:7], v[36:39], v[28:31], v[4:7]
	v_cvt_pk_bf16_f32 v55, v154, v155
	ds_read_b128 v[12:15], v180 offset:12288
	s_waitcnt lgkmcnt(3)
	v_mfma_f32_16x16x32_bf16 v[28:31], v[120:123], v[8:11], v[40:43]
	v_mfma_f32_16x16x32_bf16 v[36:39], v[120:123], v[24:27], v[48:51]
	v_add_f32_e32 v121, v190, v152
	v_add_f32_e32 v122, v176, v153
	v_cvt_pk_bf16_f32 v120, v144, v145
	v_add_u32_e32 v152, s2, v226
	ds_read_b128 v[40:43], v152 offset:16384
	s_waitcnt lgkmcnt(3)
	v_mfma_f32_16x16x32_bf16 v[48:51], v[132:135], v[8:11], v[124:127]
	v_add_f32_e32 v123, v205, v121
	v_add_f32_e32 v122, v177, v122
	v_mfma_f32_16x16x32_bf16 v[126:129], v[132:135], v[24:27], v[128:131]
	v_cvt_pk_bf16_f32 v121, v146, v147
	s_nop 2
	ds_read_b128 v[130:133], v152 offset:18432
	v_add_f32_e32 v123, v207, v123
	v_add_f32_e32 v124, v178, v122
	s_waitcnt lgkmcnt(3)
	v_mfma_f32_16x16x32_bf16 v[140:143], v[156:159], v[8:11], v[140:143]
	v_cvt_pk_bf16_f32 v122, v136, v137
	v_mfma_f32_16x16x32_bf16 v[134:137], v[156:159], v[24:27], v[148:151]
	s_nop 2
	ds_read_b128 v[146:149], v152 offset:20480
	s_waitcnt lgkmcnt(3)
	v_mfma_f32_16x16x32_bf16 v[0:3], v[12:15], v[8:11], v[0:3]
	v_add_f32_e32 v144, v208, v123
	v_add_f32_e32 v145, v179, v124
	v_mfma_f32_16x16x32_bf16 v[4:7], v[12:15], v[24:27], v[4:7]
	v_cvt_pk_bf16_f32 v123, v138, v139
	ds_read_b128 v[8:11], v152 offset:22528
	s_waitcnt lgkmcnt(3)
	v_mfma_f32_16x16x32_bf16 v[12:15], v[40:43], v[16:19], v[28:31]
	v_cvt_pk_bf16_f32 v124, v188, v189
	v_mfma_f32_16x16x32_bf16 v[24:27], v[40:43], v[32:35], v[36:39]
	v_add_u32_e32 v138, s2, v224
	s_nop 0
	ds_read_b128 v[28:31], v138 offset:16384
	s_waitcnt lgkmcnt(3)
	v_mfma_f32_16x16x32_bf16 v[36:39], v[130:133], v[16:19], v[48:51]
	v_cvt_pk_bf16_f32 v125, v191, v194
	v_mfma_f32_16x16x32_bf16 v[40:43], v[130:133], v[32:35], v[126:129]
	s_nop 1
	ds_read_b128 v[48:51], v138 offset:18432
	s_waitcnt lgkmcnt(3)
	v_mfma_f32_16x16x32_bf16 v[150:153], v[146:149], v[16:19], v[140:143]
	v_cvt_pk_bf16_f32 v126, v190, v205
	v_mfma_f32_16x16x32_bf16 v[146:149], v[146:149], v[32:35], v[134:137]
	ds_read_b128 v[154:157], v138 offset:20480
	s_waitcnt lgkmcnt(3)
	v_mfma_f32_16x16x32_bf16 v[0:3], v[8:11], v[16:19], v[0:3]
	v_cvt_pk_bf16_f32 v127, v207, v208
	v_mfma_f32_16x16x32_bf16 v[4:7], v[8:11], v[32:35], v[4:7]
	ds_read_b128 v[8:11], v138 offset:22528
	s_waitcnt lgkmcnt(3)
	v_mfma_f32_16x16x32_bf16 v[140:143], v[28:31], v[20:23], v[12:15]
	v_cvt_pk_bf16_f32 v128, v195, v202
	v_mfma_f32_16x16x32_bf16 v[136:139], v[28:31], v[44:47], v[24:27]
	s_waitcnt lgkmcnt(2)
	v_mfma_f32_16x16x32_bf16 v[32:35], v[48:51], v[20:23], v[36:39]
	v_cvt_pk_bf16_f32 v129, v203, v204
	v_mfma_f32_16x16x32_bf16 v[132:135], v[48:51], v[44:47], v[40:43]
	s_waitcnt lgkmcnt(1)
	v_mfma_f32_16x16x32_bf16 v[36:39], v[154:157], v[20:23], v[150:153]
	v_cvt_pk_bf16_f32 v130, v176, v177
	v_mfma_f32_16x16x32_bf16 v[48:51], v[154:157], v[44:47], v[146:149]
	s_waitcnt lgkmcnt(0)
	v_mfma_f32_16x16x32_bf16 v[40:43], v[8:11], v[20:23], v[0:3]
	v_cvt_pk_bf16_f32 v131, v178, v179
	v_mfma_f32_16x16x32_bf16 v[44:47], v[8:11], v[44:47], v[4:7]
	s_add_i32 s2, s9, 0
	s_add_i32 s2, s2, 0x12000
	v_add_u32_e32 v146, s2, v222
	v_add_u32_e32 v147, s2, v223
	ds_read_b64_tr_b16 v[0:1], v146
	ds_read_b64_tr_b16 v[2:3], v146 offset:4096
	ds_read_b64_tr_b16 v[4:5], v146 offset:8192
	ds_read_b64_tr_b16 v[6:7], v146 offset:12288
	ds_read_b64_tr_b16 v[8:9], v147
	ds_read_b64_tr_b16 v[10:11], v147 offset:4096
	ds_read_b64_tr_b16 v[18:19], v147 offset:4608
	ds_read_b64_tr_b16 v[16:17], v147 offset:512
	ds_read_b64_tr_b16 v[20:21], v147 offset:8192
	ds_read_b64_tr_b16 v[22:23], v147 offset:12288
	ds_read_b64_tr_b16 v[150:151], v147 offset:12800
	ds_read_b64_tr_b16 v[148:149], v147 offset:8704
	s_waitcnt lgkmcnt(6)
	v_mfma_f32_16x16x32_bf16 v[12:15], v[8:11], v[52:55], v[112:115]
	v_max_f32_e32 v24, v141, v141
	v_max_f32_e32 v25, v140, v140
	v_max_f32_e32 v24, v25, v24
	v_mfma_f32_16x16x32_bf16 v[8:11], v[8:11], v[120:123], v[116:119]
	v_max3_f32 v24, v24, v142, v143
	v_max3_f32 v24, v24, v32, v33
	v_max3_f32 v28, v24, v34, v35
	s_waitcnt lgkmcnt(2)
	v_mfma_f32_16x16x32_bf16 v[12:15], v[20:23], v[124:127], v[12:15]
	v_mfma_f32_16x16x32_bf16 v[20:23], v[20:23], v[128:131], v[8:11]
	s_nop 2
	ds_read_b64_tr_b16 v[8:9], v146 offset:512
	ds_read_b64_tr_b16 v[10:11], v146 offset:4608
	ds_read_b64_tr_b16 v[114:115], v146 offset:8704
	ds_read_b64_tr_b16 v[116:117], v146 offset:12800
	v_mfma_f32_16x16x32_bf16 v[24:27], v[0:3], v[52:55], v[108:111]
	v_max3_f32 v28, v28, v36, v37
	v_max3_f32 v28, v28, v38, v39
	v_max3_f32 v28, v28, v40, v41
	v_mfma_f32_16x16x32_bf16 v[0:3], v[0:3], v[120:123], v[104:107]
	v_max3_f32 v113, v28, v42, v43
	v_mfma_f32_16x16x32_bf16 v[24:27], v[4:7], v[124:127], v[24:27]
	v_mfma_f32_16x16x32_bf16 v[28:31], v[4:7], v[128:131], v[0:3]
	ds_read_b64_tr_b16 v[108:109], v147 offset:1024
	ds_read_b64_tr_b16 v[110:111], v147 offset:5120
	ds_read_b64_tr_b16 v[104:105], v147 offset:9216
	ds_read_b64_tr_b16 v[106:107], v147 offset:13312
	v_mfma_f32_16x16x32_bf16 v[0:3], v[16:19], v[52:55], v[96:99]
	v_mfma_f32_16x16x32_bf16 v[4:7], v[16:19], v[120:123], v[100:103]
	v_max_f32_e32 v16, v137, v137
	v_max_f32_e32 v17, v136, v136
	v_max_f32_e32 v16, v17, v16
	s_waitcnt lgkmcnt(8)
	v_mfma_f32_16x16x32_bf16 v[0:3], v[148:151], v[124:127], v[0:3]
	v_max3_f32 v16, v16, v138, v139
	v_max3_f32 v16, v16, v132, v133
	v_max3_f32 v112, v16, v134, v135
	v_mfma_f32_16x16x32_bf16 v[4:7], v[148:151], v[128:131], v[4:7]
	ds_read_b64_tr_b16 v[100:101], v146 offset:1024
	ds_read_b64_tr_b16 v[102:103], v146 offset:5120
	ds_read_b64_tr_b16 v[96:97], v146 offset:9216
	ds_read_b64_tr_b16 v[98:99], v146 offset:13312
	s_waitcnt lgkmcnt(10)
	v_mfma_f32_16x16x32_bf16 v[16:19], v[8:11], v[52:55], v[92:95]
	v_mfma_f32_16x16x32_bf16 v[90:93], v[8:11], v[120:123], v[88:91]
	s_waitcnt lgkmcnt(8)
	v_mfma_f32_16x16x32_bf16 v[8:11], v[114:117], v[124:127], v[16:19]
	s_nop 5
	v_max3_f32 v16, v112, v48, v49
	v_max3_f32 v16, v16, v50, v51
	v_max3_f32 v16, v16, v44, v45
	v_max3_f32 v88, v16, v46, v47
	v_mfma_f32_16x16x32_bf16 v[16:19], v[114:117], v[128:131], v[90:93]
	v_max_f32_e32 v89, v113, v88
	v_cmp_ge_f32_e32 vcc, s62, v89
	s_cmp_lg_u64 vcc, exec
	s_cselect_b64 s[6:7], -1, 0
	s_cmp_eq_u64 vcc, exec
	v_mov_b32_e32 v112, 1.0
	s_cbranch_scc1 .LBB0_981
	ds_bpermute_b32 v89, v220, v113
	v_max_f32_e32 v90, v113, v113
	s_waitcnt lgkmcnt(0)
	v_max_f32_e32 v89, v89, v89
	v_max_f32_e32 v89, v90, v89
	ds_bpermute_b32 v90, v221, v89
	s_waitcnt lgkmcnt(0)
	v_max3_f32 v89, v89, v90, 0
	ds_bpermute_b32 v90, v220, v88
	v_max_f32_e32 v88, v88, v88
	v_exp_f32_e64 v114, -v89
	v_sub_f32_e32 v140, v140, v89
	v_sub_f32_e32 v141, v141, v89
	s_waitcnt lgkmcnt(0)
	v_max_f32_e32 v90, v90, v90
	v_max_f32_e32 v88, v88, v90
	ds_bpermute_b32 v90, v221, v88
	v_sub_f32_e32 v142, v142, v89
	v_sub_f32_e32 v143, v143, v89
	v_sub_f32_e32 v32, v32, v89
	v_sub_f32_e32 v33, v33, v89
	s_waitcnt lgkmcnt(0)
	v_max3_f32 v88, v88, v90, 0
	v_exp_f32_e64 v112, -v88
	v_sub_f32_e32 v34, v34, v89
	v_sub_f32_e32 v35, v35, v89
	v_sub_f32_e32 v39, v39, v89
	v_sub_f32_e32 v38, v38, v89
	v_sub_f32_e32 v37, v37, v89
	v_sub_f32_e32 v36, v36, v89
	v_sub_f32_e32 v43, v43, v89
	v_sub_f32_e32 v42, v42, v89
	v_sub_f32_e32 v41, v41, v89
	v_sub_f32_e32 v40, v40, v89
	v_sub_f32_e32 v136, v136, v88
	v_sub_f32_e32 v137, v137, v88
	v_sub_f32_e32 v138, v138, v88
	v_sub_f32_e32 v139, v139, v88
	v_sub_f32_e32 v132, v132, v88
	v_sub_f32_e32 v133, v133, v88
	v_sub_f32_e32 v134, v134, v88
	v_sub_f32_e32 v135, v135, v88
	v_sub_f32_e32 v51, v51, v88
	v_sub_f32_e32 v50, v50, v88
	v_sub_f32_e32 v49, v49, v88
	v_sub_f32_e32 v48, v48, v88
	v_sub_f32_e32 v47, v47, v88
	v_sub_f32_e32 v46, v46, v88
	v_sub_f32_e32 v45, v45, v88
	v_sub_f32_e32 v44, v44, v88
	s_branch .LBB0_982

.LBB0_982:
	ds_read_b64_tr_b16 v[116:117], v147 offset:1536
	ds_read_b64_tr_b16 v[118:119], v147 offset:5632
	ds_read_b64_tr_b16 v[148:149], v147 offset:9728
	ds_read_b64_tr_b16 v[150:151], v147 offset:13824
	v_mov_b32_e32 v198, 0x358637bd
	v_mov_b32_e32 v199, 0x260
	v_mov_b32_e32 v214, 1
	v_mov_b64_e32 v[222:223], 0x1e8481
	v_mov_b32_e32 v215, 0x2c00
	s_waitcnt lgkmcnt(10)
	v_mfma_f32_16x16x32_bf16 v[80:83], v[108:111], v[52:55], v[80:83]
	v_exp_f32_e32 v92, v140
	v_exp_f32_e32 v93, v141
	v_exp_f32_e32 v94, v142
	v_mfma_f32_16x16x32_bf16 v[84:87], v[108:111], v[120:123], v[84:87]
	v_exp_f32_e32 v95, v143
	s_waitcnt lgkmcnt(8)
	v_mfma_f32_16x16x32_bf16 v[80:83], v[104:107], v[124:127], v[80:83]
	v_mfma_f32_16x16x32_bf16 v[84:87], v[104:107], v[128:131], v[84:87]
	ds_read_b64_tr_b16 v[104:105], v146 offset:1536
	ds_read_b64_tr_b16 v[106:107], v146 offset:5632
	ds_read_b64_tr_b16 v[108:109], v146 offset:9728
	ds_read_b64_tr_b16 v[110:111], v146 offset:13824
	s_waitcnt lgkmcnt(10)
	v_mfma_f32_16x16x32_bf16 v[72:75], v[100:103], v[52:55], v[72:75]
	v_exp_f32_e32 v88, v136
	v_exp_f32_e32 v89, v137
	v_exp_f32_e32 v90, v138
	v_mfma_f32_16x16x32_bf16 v[76:79], v[100:103], v[120:123], v[76:79]
	v_exp_f32_e32 v91, v139
	s_waitcnt lgkmcnt(8)
	v_mfma_f32_16x16x32_bf16 v[72:75], v[96:99], v[124:127], v[72:75]
	v_mfma_f32_16x16x32_bf16 v[76:79], v[96:99], v[128:131], v[76:79]
	s_waitcnt lgkmcnt(6)
	v_mfma_f32_16x16x32_bf16 v[64:67], v[116:119], v[52:55], v[64:67]
	v_exp_f32_e32 v96, v32
	v_exp_f32_e32 v97, v33
	v_exp_f32_e32 v98, v34
	v_mfma_f32_16x16x32_bf16 v[68:71], v[116:119], v[120:123], v[68:71]
	v_exp_f32_e32 v99, v35
	s_waitcnt lgkmcnt(4)
	v_mfma_f32_16x16x32_bf16 v[64:67], v[148:151], v[124:127], v[64:67]
	v_mfma_f32_16x16x32_bf16 v[68:71], v[148:151], v[128:131], v[68:71]
	s_waitcnt lgkmcnt(2)
	v_mfma_f32_16x16x32_bf16 v[32:35], v[104:107], v[52:55], v[56:59]
	s_and_b64 vcc, exec, s[6:7]
	v_mfma_f32_16x16x32_bf16 v[52:55], v[104:107], v[120:123], v[60:63]
	s_nop 0
	v_exp_f32_e32 v56, v132
	v_exp_f32_e32 v57, v133
	v_exp_f32_e32 v58, v134
	s_waitcnt lgkmcnt(0)
	v_mfma_f32_16x16x32_bf16 v[32:35], v[108:111], v[124:127], v[32:35]
	v_exp_f32_e32 v59, v135
	v_mfma_f32_16x16x32_bf16 v[52:55], v[108:111], v[128:131], v[52:55]
	s_cbranch_vccz .LBB0_985
	v_max_f32_e32 v60, v112, v112
	v_max_f32_e32 v61, v114, v114
	v_min_f32_e32 v60, v61, v60
	v_cmp_gt_f32_e32 vcc, 1.0, v60
	s_cbranch_vccz .LBB0_985
	v_pk_mul_f32 v[14:15], v[14:15], v[114:115] op_sel_hi:[1,0]
	v_pk_mul_f32 v[12:13], v[12:13], v[114:115] op_sel_hi:[1,0]
	v_pk_mul_f32 v[26:27], v[26:27], v[114:115] op_sel_hi:[1,0]
	v_pk_mul_f32 v[24:25], v[24:25], v[114:115] op_sel_hi:[1,0]
	v_pk_mul_f32 v[2:3], v[2:3], v[114:115] op_sel_hi:[1,0]
	v_pk_mul_f32 v[0:1], v[0:1], v[114:115] op_sel_hi:[1,0]
	v_pk_mul_f32 v[10:11], v[10:11], v[114:115] op_sel_hi:[1,0]
	v_pk_mul_f32 v[8:9], v[8:9], v[114:115] op_sel_hi:[1,0]
	v_pk_mul_f32 v[82:83], v[114:115], v[82:83] op_sel_hi:[0,1]
	v_pk_mul_f32 v[80:81], v[114:115], v[80:81] op_sel_hi:[0,1]
	v_pk_mul_f32 v[74:75], v[114:115], v[74:75] op_sel_hi:[0,1]
	v_pk_mul_f32 v[72:73], v[114:115], v[72:73] op_sel_hi:[0,1]
	v_pk_mul_f32 v[66:67], v[114:115], v[66:67] op_sel_hi:[0,1]
	v_pk_mul_f32 v[64:65], v[114:115], v[64:65] op_sel_hi:[0,1]
	v_pk_mul_f32 v[34:35], v[114:115], v[34:35] op_sel_hi:[0,1]
	v_pk_mul_f32 v[32:33], v[114:115], v[32:33] op_sel_hi:[0,1]
	v_pk_mul_f32 v[22:23], v[22:23], v[112:113] op_sel_hi:[1,0]
	v_pk_mul_f32 v[20:21], v[20:21], v[112:113] op_sel_hi:[1,0]
	v_pk_mul_f32 v[30:31], v[30:31], v[112:113] op_sel_hi:[1,0]
	v_pk_mul_f32 v[28:29], v[28:29], v[112:113] op_sel_hi:[1,0]
	v_pk_mul_f32 v[6:7], v[6:7], v[112:113] op_sel_hi:[1,0]
	v_pk_mul_f32 v[4:5], v[4:5], v[112:113] op_sel_hi:[1,0]
	v_pk_mul_f32 v[18:19], v[18:19], v[112:113] op_sel_hi:[1,0]
	v_pk_mul_f32 v[16:17], v[16:17], v[112:113] op_sel_hi:[1,0]
	v_pk_mul_f32 v[86:87], v[112:113], v[86:87] op_sel_hi:[0,1]
	v_pk_mul_f32 v[84:85], v[112:113], v[84:85] op_sel_hi:[0,1]
	v_pk_mul_f32 v[78:79], v[112:113], v[78:79] op_sel_hi:[0,1]
	v_pk_mul_f32 v[76:77], v[112:113], v[76:77] op_sel_hi:[0,1]
	v_pk_mul_f32 v[70:71], v[112:113], v[70:71] op_sel_hi:[0,1]
	v_pk_mul_f32 v[68:69], v[112:113], v[68:69] op_sel_hi:[0,1]
	v_pk_mul_f32 v[54:55], v[112:113], v[54:55] op_sel_hi:[0,1]
	v_pk_mul_f32 v[52:53], v[112:113], v[52:53] op_sel_hi:[0,1]
